# v18 + P10 table row loads issued with agent-scope (sc1) cache policy: the 34 MB of rows per layer no longer churn the 4 MB L2
# baseline (speedup 1.0000x reference)
; __device__ __forceinline__ void peer_gather(const Frame& F, int l) {
;     ...
;     for (int t = F.bid * NWAVES + F.wave; t < M; t += F.G * NWAVES) {
;         asm volatile("" : "+v"(lane));
;         int e0 = ((const int*)(ws + WS_EID))[(size_t)t * 128 + lane], e1 = ((const int*)(ws + WS_EID))[(size_t)t * 128 + 64 + lane];
;         const float w0 = ((const float*)(ws + WS_GW))[(size_t)t * 128 + lane], w1 = ((const float*)(ws + WS_GW))[(size_t)t * 128 + 64 + lane];
;         u32x4 xw4[4];
; #pragma unroll
;         for (int q = 0; q < 4; ++q) xw4[q] = *(const u32x4*)(XBp + (size_t)t * D + 32 * lane + 8 * q);
;         asm volatile("" : "+v"(e0), "+v"(e1));
;         f32x2 xp[16];
;         f32x2 acc[16];
; #pragma unroll
;         for (int j = 0; j < 16; ++j) acc[j] = (f32x2){0.f, 0.f};
;         u32x4 rr[16]; float rsc[16];
;     ...
; #pragma unroll
;         for (int s = 0; s < 15; ++s) PG_STEP(s, 0);
.Lp10_have_ew:
	s_add_u32 s0, s33, s28
	s_addc_u32 s1, s34, s29
	v_lshl_add_u64 v[0:1], v[94:95], 1, s[0:1]
	global_load_dwordx4 v[150:153], v[0:1], off offset:48
	global_load_dwordx4 v[154:157], v[0:1], off offset:32
	global_load_dwordx4 v[158:161], v[0:1], off offset:16
	global_load_dwordx4 v[162:165], v[0:1], off
	s_waitcnt vmcnt(4)
	v_mov_b32_e32 v167, v198
	v_mov_b32_e32 v168, v199
	v_mov_b32_e32 v169, v200
	v_mov_b32_e32 v170, v166
	s_add_i32 s0, s8, s37
	s_cmpk_lt_i32 s0, 0x2800
	s_cselect_b32 s0, s0, s8
	s_ashr_i32 s1, s0, 31
	s_lshl_b64 s[0:1], s[0:1], 7
	v_lshl_add_u64 v[190:191], s[0:1], 0, v[92:93]
	v_lshlrev_b64 v[190:191], 2, v[190:191]
	v_lshl_add_u64 v[0:1], s[22:23], 0, v[190:191]
	global_load_dword v198, v[0:1], off
	global_load_dword v199, v[0:1], off offset:256
	v_lshl_add_u64 v[0:1], s[24:25], 0, v[190:191]
	global_load_dword v200, v[0:1], off
	global_load_dword v166, v[0:1], off offset:256
	v_lshlrev_b32_e32 v196, 4, v92
	v_add_u32_e32 v194, 8, v92
	v_and_b32_e32 v194, 63, v194
	v_lshlrev_b32_e32 v194, 2, v194
	v_xor_b32_e32 v197, 16, v92
	v_lshlrev_b32_e32 v197, 2, v197
	v_xor_b32_e32 v89, 32, v92
	v_lshlrev_b32_e32 v89, 2, v89
	v_xor_b32_e32 v90, 48, v92
	v_lshlrev_b32_e32 v90, 2, v90
	ds_bpermute_b32 v192, v194, v167
	v_mov_b32_e32 v193, v169
	s_mov_b32 vcc_lo, 0xaaaaaaaa
	s_mov_b32 vcc_hi, 0xaaaaaaaa
	s_mov_b32 s100, 0xcccccccc
	s_mov_b32 s101, 0xcccccccc
	v_readlane_b32 s0, v167, 0
	v_readlane_b32 s1, v167, 1
	v_readlane_b32 s4, v167, 2
	v_readlane_b32 s5, v167, 3
	v_readlane_b32 s6, v167, 4
	v_readlane_b32 s7, v167, 5
	v_readlane_b32 s58, v167, 6
	v_readlane_b32 s59, v167, 7
	s_nop 1
	v_lshl_add_u32 v87, s0, 10, v196
	v_lshl_add_u32 v88, s0, 7, v92
	global_load_dwordx4 v[0:3], v87, s[12:13] sc1
	global_load_ubyte v64, v88, s[14:15]
	v_lshl_add_u32 v87, s1, 10, v196
	v_lshl_add_u32 v88, s1, 7, v92
	global_load_dwordx4 v[4:7], v87, s[12:13] sc1
	global_load_ubyte v65, v88, s[14:15]
	v_lshl_add_u32 v87, s4, 10, v196
	v_lshl_add_u32 v88, s4, 7, v92
	global_load_dwordx4 v[8:11], v87, s[12:13] sc1
	global_load_ubyte v66, v88, s[14:15]
	v_lshl_add_u32 v87, s5, 10, v196
	v_lshl_add_u32 v88, s5, 7, v92
	global_load_dwordx4 v[12:15], v87, s[12:13] sc1
	global_load_ubyte v67, v88, s[14:15]
	v_lshl_add_u32 v87, s6, 10, v196
	v_lshl_add_u32 v88, s6, 7, v92
	global_load_dwordx4 v[16:19], v87, s[12:13] sc1
	global_load_ubyte v68, v88, s[14:15]
	v_lshl_add_u32 v87, s7, 10, v196
	v_lshl_add_u32 v88, s7, 7, v92
	global_load_dwordx4 v[20:23], v87, s[12:13] sc1
	global_load_ubyte v69, v88, s[14:15]
	v_lshl_add_u32 v87, s58, 10, v196
	v_lshl_add_u32 v88, s58, 7, v92
	global_load_dwordx4 v[24:27], v87, s[12:13] sc1
	global_load_ubyte v70, v88, s[14:15]
	v_lshl_add_u32 v87, s59, 10, v196
	v_lshl_add_u32 v88, s59, 7, v92
	global_load_dwordx4 v[28:31], v87, s[12:13] sc1
	global_load_ubyte v71, v88, s[14:15]
	v_lshl_add_u32 v87, s0, 10, v196
	v_lshl_add_u32 v88, s0, 7, v92
	global_load_dwordx4 v[32:35], v87, s[16:17] sc1
	global_load_ubyte v72, v88, s[14:15] offset:64
	v_lshl_add_u32 v87, s1, 10, v196
	v_lshl_add_u32 v88, s1, 7, v92
	global_load_dwordx4 v[36:39], v87, s[16:17] sc1
	global_load_ubyte v73, v88, s[14:15] offset:64
	v_lshl_add_u32 v87, s4, 10, v196
	v_lshl_add_u32 v88, s4, 7, v92
	global_load_dwordx4 v[40:43], v87, s[16:17] sc1
	global_load_ubyte v74, v88, s[14:15] offset:64
	v_lshl_add_u32 v87, s5, 10, v196
	v_lshl_add_u32 v88, s5, 7, v92
	global_load_dwordx4 v[44:47], v87, s[16:17] sc1
	global_load_ubyte v75, v88, s[14:15] offset:64
	v_lshl_add_u32 v87, s6, 10, v196
	v_lshl_add_u32 v88, s6, 7, v92
	global_load_dwordx4 v[48:51], v87, s[16:17] sc1
	global_load_ubyte v76, v88, s[14:15] offset:64
	v_lshl_add_u32 v87, s7, 10, v196
	v_lshl_add_u32 v88, s7, 7, v92
	global_load_dwordx4 v[52:55], v87, s[16:17] sc1
	global_load_ubyte v77, v88, s[14:15] offset:64
	v_lshl_add_u32 v87, s58, 10, v196
	v_lshl_add_u32 v88, s58, 7, v92
	global_load_dwordx4 v[56:59], v87, s[16:17] sc1
	global_load_ubyte v78, v88, s[14:15] offset:64
	v_lshl_add_u32 v87, s59, 10, v196
	v_lshl_add_u32 v88, s59, 7, v92
	global_load_dwordx4 v[60:63], v87, s[16:17] sc1
	global_load_ubyte v79, v88, s[14:15] offset:64
	s_waitcnt vmcnt(36)
	v_lshlrev_b32_e32 v132, 16, v162
	v_and_b32_e32 v133, 0xffff0000, v162
	v_lshlrev_b32_e32 v130, 16, v163
	v_and_b32_e32 v131, 0xffff0000, v163
	v_lshlrev_b32_e32 v128, 16, v164
	v_and_b32_e32 v129, 0xffff0000, v164
	v_lshlrev_b32_e32 v126, 16, v165
	v_and_b32_e32 v127, 0xffff0000, v165
	v_lshlrev_b32_e32 v124, 16, v158
	v_and_b32_e32 v125, 0xffff0000, v158
	v_lshlrev_b32_e32 v122, 16, v159
	v_and_b32_e32 v123, 0xffff0000, v159
	v_lshlrev_b32_e32 v120, 16, v160
	v_and_b32_e32 v121, 0xffff0000, v160
	v_lshlrev_b32_e32 v118, 16, v161
	v_and_b32_e32 v119, 0xffff0000, v161
	v_lshlrev_b32_e32 v116, 16, v154
	v_and_b32_e32 v117, 0xffff0000, v154
	v_lshlrev_b32_e32 v114, 16, v155
	v_and_b32_e32 v115, 0xffff0000, v155
	v_lshlrev_b32_e32 v112, 16, v156
	v_and_b32_e32 v113, 0xffff0000, v156
	v_lshlrev_b32_e32 v110, 16, v157
	v_and_b32_e32 v111, 0xffff0000, v157
	v_lshlrev_b32_e32 v106, 16, v150
	v_and_b32_e32 v107, 0xffff0000, v150
	v_lshlrev_b32_e32 v108, 16, v151
	v_and_b32_e32 v109, 0xffff0000, v151
	v_lshlrev_b32_e32 v104, 16, v152
	v_and_b32_e32 v105, 0xffff0000, v152
	v_lshlrev_b32_e32 v102, 16, v153
	v_and_b32_e32 v103, 0xffff0000, v153
	v_mov_b32_e32 v164, 0
	v_mov_b32_e32 v165, 0
	v_mov_b32_e32 v162, 0
	v_mov_b32_e32 v163, 0
	v_mov_b32_e32 v160, 0
	v_mov_b32_e32 v161, 0
	v_mov_b32_e32 v158, 0
	v_mov_b32_e32 v159, 0
	v_mov_b32_e32 v156, 0
	v_mov_b32_e32 v157, 0
	v_mov_b32_e32 v154, 0
	v_mov_b32_e32 v155, 0
	v_mov_b32_e32 v152, 0
	v_mov_b32_e32 v153, 0
	v_mov_b32_e32 v150, 0
	v_mov_b32_e32 v151, 0
	v_mov_b32_e32 v148, 0
	v_mov_b32_e32 v149, 0
	v_mov_b32_e32 v146, 0
	v_mov_b32_e32 v147, 0
	v_mov_b32_e32 v144, 0
	v_mov_b32_e32 v145, 0
	v_mov_b32_e32 v142, 0
	v_mov_b32_e32 v143, 0
	v_mov_b32_e32 v140, 0
	v_mov_b32_e32 v141, 0
	v_mov_b32_e32 v138, 0
	v_mov_b32_e32 v139, 0
	v_mov_b32_e32 v136, 0
	v_mov_b32_e32 v137, 0
	v_mov_b32_e32 v134, 0
	v_mov_b32_e32 v135, 0
	s_mov_b32 s30, 0
	s_waitcnt lgkmcnt(0)
; __device__ __forceinline__ float gelu_tanh(float x) { const float u = 0.7978845608028654f * (x + 0.044715f * x * x * x); const float e = __expf(2.0f * u); return 0.5f * x * (2.0f - 2.0f * frcp(e + 1.0f)); }
; __device__ __forceinline__ void peer_gather(const Frame& F, int l) {
;     ...
;         for (int it = 0; it < 16; ++it) {
;             const int eb = 8 * it;
;             float cf[4];
; #pragma unroll
;             for (int s = 0; s < 16; ++s) {
;                 asm volatile("" ::: "memory");
;                 if (s == 0) PG_STEP(15, eb); else if (it < 15) PG_STEP(s - 1, eb + 8);
;                 asm volatile("" ::: "memory");
;                 const int g = s >> 3, k = s & 7;
;                 const float bsc = __uint_as_float(__float_as_uint(rsc[s]) << 23);
;                 if (k < 4) {
;                     f32x2 d2 = (f32x2){0.f, 0.f};
; #pragma unroll
;                     for (int i = 0; i < 4; ++i) { const unsigned w = rr[s][i];
;                         d2 += xp[4 * i + 0] * __builtin_amdgcn_cvt_scalef32_pk_f32_fp4(w, bsc, 0); d2 += xp[4 * i + 1] * __builtin_amdgcn_cvt_scalef32_pk_f32_fp4(w, bsc, 1);
;                         d2 += xp[4 * i + 2] * __builtin_amdgcn_cvt_scalef32_pk_f32_fp4(w, bsc, 2); d2 += xp[4 * i + 3] * __builtin_amdgcn_cvt_scalef32_pk_f32_fp4(w, bsc, 3); }
;                     const float act = wave_sum_dpp(d2[0] + d2[1]);
;                     const int idx = eb + 4 * g + k;
;                     const float gwt = __uint_as_float(idx < 64 ? __builtin_amdgcn_readlane(__float_as_uint(w0), idx) : __builtin_amdgcn_readlane(__float_as_uint(w1), idx - 64));
;                     cf[k] = gwt * gelu_tanh(act);
.Lp10_blk:
	v_readlane_b32 s0, v192, 0
	v_readlane_b32 s1, v192, 1
	v_readlane_b32 s4, v192, 2
	v_readlane_b32 s5, v192, 3
	v_readlane_b32 s6, v192, 4
	v_readlane_b32 s7, v192, 5
	v_readlane_b32 s58, v192, 6
	v_readlane_b32 s59, v192, 7
	s_waitcnt vmcnt(30)
	v_lshlrev_b32_e32 v86, 23, v64
	v_cvt_scalef32_pk_f32_fp4 v[80:81], v0, v86
	v_cvt_scalef32_pk_f32_fp4 v[82:83], v0, v86 op_sel:[1,0,0]
	v_pk_mul_f32 v[84:85], v[80:81], v[132:133]
	v_cvt_scalef32_pk_f32_fp4 v[80:81], v0, v86 op_sel:[0,1,0]
	v_pk_fma_f32 v[84:85], v[82:83], v[130:131], v[84:85]
	v_cvt_scalef32_pk_f32_fp4 v[82:83], v0, v86 op_sel:[1,1,0]
	v_pk_fma_f32 v[84:85], v[80:81], v[128:129], v[84:85]
	v_cvt_scalef32_pk_f32_fp4 v[80:81], v1, v86
	v_pk_fma_f32 v[84:85], v[82:83], v[126:127], v[84:85]
	v_cvt_scalef32_pk_f32_fp4 v[82:83], v1, v86 op_sel:[1,0,0]
	v_pk_fma_f32 v[84:85], v[80:81], v[124:125], v[84:85]
	v_cvt_scalef32_pk_f32_fp4 v[80:81], v1, v86 op_sel:[0,1,0]
	v_pk_fma_f32 v[84:85], v[82:83], v[122:123], v[84:85]
	v_cvt_scalef32_pk_f32_fp4 v[82:83], v1, v86 op_sel:[1,1,0]
	v_pk_fma_f32 v[84:85], v[80:81], v[120:121], v[84:85]
	v_cvt_scalef32_pk_f32_fp4 v[80:81], v2, v86
	v_pk_fma_f32 v[84:85], v[82:83], v[118:119], v[84:85]
	v_cvt_scalef32_pk_f32_fp4 v[82:83], v2, v86 op_sel:[1,0,0]
	v_pk_fma_f32 v[84:85], v[80:81], v[116:117], v[84:85]
	v_cvt_scalef32_pk_f32_fp4 v[80:81], v2, v86 op_sel:[0,1,0]
	v_pk_fma_f32 v[84:85], v[82:83], v[114:115], v[84:85]
	v_cvt_scalef32_pk_f32_fp4 v[82:83], v2, v86 op_sel:[1,1,0]
	v_pk_fma_f32 v[84:85], v[80:81], v[112:113], v[84:85]
	v_cvt_scalef32_pk_f32_fp4 v[80:81], v3, v86
	v_pk_fma_f32 v[84:85], v[82:83], v[110:111], v[84:85]
	v_cvt_scalef32_pk_f32_fp4 v[82:83], v3, v86 op_sel:[1,0,0]
	v_pk_fma_f32 v[84:85], v[80:81], v[106:107], v[84:85]
	v_cvt_scalef32_pk_f32_fp4 v[80:81], v3, v86 op_sel:[0,1,0]
	v_pk_fma_f32 v[84:85], v[82:83], v[108:109], v[84:85]
	v_cvt_scalef32_pk_f32_fp4 v[82:83], v3, v86 op_sel:[1,1,0]
	v_pk_fma_f32 v[84:85], v[80:81], v[104:105], v[84:85]
	v_pk_fma_f32 v[84:85], v[82:83], v[102:103], v[84:85]
	v_add_f32_e32 v171, v84, v85
	v_lshl_add_u32 v87, s0, 10, v196
	v_lshl_add_u32 v88, s0, 7, v92
	global_load_dwordx4 v[0:3], v87, s[12:13] sc1
	global_load_ubyte v64, v88, s[14:15]
	s_waitcnt vmcnt(30)
	v_lshlrev_b32_e32 v86, 23, v65
	v_cvt_scalef32_pk_f32_fp4 v[80:81], v4, v86
	v_cvt_scalef32_pk_f32_fp4 v[82:83], v4, v86 op_sel:[1,0,0]
	v_pk_mul_f32 v[84:85], v[80:81], v[132:133]
	v_cvt_scalef32_pk_f32_fp4 v[80:81], v4, v86 op_sel:[0,1,0]
	v_pk_fma_f32 v[84:85], v[82:83], v[130:131], v[84:85]
	v_cvt_scalef32_pk_f32_fp4 v[82:83], v4, v86 op_sel:[1,1,0]
	v_pk_fma_f32 v[84:85], v[80:81], v[128:129], v[84:85]
	v_cvt_scalef32_pk_f32_fp4 v[80:81], v5, v86
	v_pk_fma_f32 v[84:85], v[82:83], v[126:127], v[84:85]
	v_cvt_scalef32_pk_f32_fp4 v[82:83], v5, v86 op_sel:[1,0,0]
	v_pk_fma_f32 v[84:85], v[80:81], v[124:125], v[84:85]
	v_cvt_scalef32_pk_f32_fp4 v[80:81], v5, v86 op_sel:[0,1,0]
	v_pk_fma_f32 v[84:85], v[82:83], v[122:123], v[84:85]
	v_cvt_scalef32_pk_f32_fp4 v[82:83], v5, v86 op_sel:[1,1,0]
	v_pk_fma_f32 v[84:85], v[80:81], v[120:121], v[84:85]
	v_cvt_scalef32_pk_f32_fp4 v[80:81], v6, v86
	v_pk_fma_f32 v[84:85], v[82:83], v[118:119], v[84:85]
	v_cvt_scalef32_pk_f32_fp4 v[82:83], v6, v86 op_sel:[1,0,0]
	v_pk_fma_f32 v[84:85], v[80:81], v[116:117], v[84:85]
	v_cvt_scalef32_pk_f32_fp4 v[80:81], v6, v86 op_sel:[0,1,0]
	v_pk_fma_f32 v[84:85], v[82:83], v[114:115], v[84:85]
	v_cvt_scalef32_pk_f32_fp4 v[82:83], v6, v86 op_sel:[1,1,0]
	v_pk_fma_f32 v[84:85], v[80:81], v[112:113], v[84:85]
	v_cvt_scalef32_pk_f32_fp4 v[80:81], v7, v86
	v_pk_fma_f32 v[84:85], v[82:83], v[110:111], v[84:85]
	v_cvt_scalef32_pk_f32_fp4 v[82:83], v7, v86 op_sel:[1,0,0]
	v_pk_fma_f32 v[84:85], v[80:81], v[106:107], v[84:85]
	v_cvt_scalef32_pk_f32_fp4 v[80:81], v7, v86 op_sel:[0,1,0]
	v_pk_fma_f32 v[84:85], v[82:83], v[108:109], v[84:85]
	v_cvt_scalef32_pk_f32_fp4 v[82:83], v7, v86 op_sel:[1,1,0]
	v_pk_fma_f32 v[84:85], v[80:81], v[104:105], v[84:85]
	v_pk_fma_f32 v[84:85], v[82:83], v[102:103], v[84:85]
	v_add_f32_e32 v172, v84, v85
	v_lshl_add_u32 v87, s1, 10, v196
	v_lshl_add_u32 v88, s1, 7, v92
	global_load_dwordx4 v[4:7], v87, s[12:13] sc1
	global_load_ubyte v65, v88, s[14:15]
	s_waitcnt vmcnt(30)
	v_lshlrev_b32_e32 v86, 23, v66
	v_cvt_scalef32_pk_f32_fp4 v[80:81], v8, v86
	v_cvt_scalef32_pk_f32_fp4 v[82:83], v8, v86 op_sel:[1,0,0]
	v_pk_mul_f32 v[84:85], v[80:81], v[132:133]
	v_cvt_scalef32_pk_f32_fp4 v[80:81], v8, v86 op_sel:[0,1,0]
	v_pk_fma_f32 v[84:85], v[82:83], v[130:131], v[84:85]
	v_cvt_scalef32_pk_f32_fp4 v[82:83], v8, v86 op_sel:[1,1,0]
	v_pk_fma_f32 v[84:85], v[80:81], v[128:129], v[84:85]
	v_cvt_scalef32_pk_f32_fp4 v[80:81], v9, v86
	v_pk_fma_f32 v[84:85], v[82:83], v[126:127], v[84:85]
	v_cvt_scalef32_pk_f32_fp4 v[82:83], v9, v86 op_sel:[1,0,0]
	v_pk_fma_f32 v[84:85], v[80:81], v[124:125], v[84:85]
	v_cvt_scalef32_pk_f32_fp4 v[80:81], v9, v86 op_sel:[0,1,0]
	v_pk_fma_f32 v[84:85], v[82:83], v[122:123], v[84:85]
	v_cvt_scalef32_pk_f32_fp4 v[82:83], v9, v86 op_sel:[1,1,0]
	v_pk_fma_f32 v[84:85], v[80:81], v[120:121], v[84:85]
	v_cvt_scalef32_pk_f32_fp4 v[80:81], v10, v86
	v_pk_fma_f32 v[84:85], v[82:83], v[118:119], v[84:85]
	v_cvt_scalef32_pk_f32_fp4 v[82:83], v10, v86 op_sel:[1,0,0]
	v_pk_fma_f32 v[84:85], v[80:81], v[116:117], v[84:85]
	v_cvt_scalef32_pk_f32_fp4 v[80:81], v10, v86 op_sel:[0,1,0]
	v_pk_fma_f32 v[84:85], v[82:83], v[114:115], v[84:85]
	v_cvt_scalef32_pk_f32_fp4 v[82:83], v10, v86 op_sel:[1,1,0]
	v_pk_fma_f32 v[84:85], v[80:81], v[112:113], v[84:85]
	v_cvt_scalef32_pk_f32_fp4 v[80:81], v11, v86
	v_pk_fma_f32 v[84:85], v[82:83], v[110:111], v[84:85]
	v_cvt_scalef32_pk_f32_fp4 v[82:83], v11, v86 op_sel:[1,0,0]
	v_pk_fma_f32 v[84:85], v[80:81], v[106:107], v[84:85]
	v_cvt_scalef32_pk_f32_fp4 v[80:81], v11, v86 op_sel:[0,1,0]
	v_pk_fma_f32 v[84:85], v[82:83], v[108:109], v[84:85]
	v_cvt_scalef32_pk_f32_fp4 v[82:83], v11, v86 op_sel:[1,1,0]
	v_pk_fma_f32 v[84:85], v[80:81], v[104:105], v[84:85]
	v_pk_fma_f32 v[84:85], v[82:83], v[102:103], v[84:85]
	v_add_f32_e32 v173, v84, v85
	v_lshl_add_u32 v87, s4, 10, v196
	v_lshl_add_u32 v88, s4, 7, v92
	global_load_dwordx4 v[8:11], v87, s[12:13] sc1
	global_load_ubyte v66, v88, s[14:15]
	s_waitcnt vmcnt(30)
; __device__ __forceinline__ float gelu_tanh(float x) { const float u = 0.7978845608028654f * (x + 0.044715f * x * x * x); const float e = __expf(2.0f * u); return 0.5f * x * (2.0f - 2.0f * frcp(e + 1.0f)); }
; __device__ __forceinline__ void peer_gather(const Frame& F, int l) {
;     ...
;         for (int it = 0; it < 16; ++it) {
;             const int eb = 8 * it;
;             float cf[4];
; #pragma unroll
;             for (int s = 0; s < 16; ++s) {
;                 asm volatile("" ::: "memory");
;                 if (s == 0) PG_STEP(15, eb); else if (it < 15) PG_STEP(s - 1, eb + 8);
;                 asm volatile("" ::: "memory");
;                 const int g = s >> 3, k = s & 7;
;                 const float bsc = __uint_as_float(__float_as_uint(rsc[s]) << 23);
;                 if (k < 4) {
;                     f32x2 d2 = (f32x2){0.f, 0.f};
; #pragma unroll
;                     for (int i = 0; i < 4; ++i) { const unsigned w = rr[s][i];
;                         d2 += xp[4 * i + 0] * __builtin_amdgcn_cvt_scalef32_pk_f32_fp4(w, bsc, 0); d2 += xp[4 * i + 1] * __builtin_amdgcn_cvt_scalef32_pk_f32_fp4(w, bsc, 1);
;                         d2 += xp[4 * i + 2] * __builtin_amdgcn_cvt_scalef32_pk_f32_fp4(w, bsc, 2); d2 += xp[4 * i + 3] * __builtin_amdgcn_cvt_scalef32_pk_f32_fp4(w, bsc, 3); }
;                     const float act = wave_sum_dpp(d2[0] + d2[1]);
;                     const int idx = eb + 4 * g + k;
;                     const float gwt = __uint_as_float(idx < 64 ? __builtin_amdgcn_readlane(__float_as_uint(w0), idx) : __builtin_amdgcn_readlane(__float_as_uint(w1), idx - 64));
;                     cf[k] = gwt * gelu_tanh(act);
	v_lshlrev_b32_e32 v86, 23, v67
	v_cvt_scalef32_pk_f32_fp4 v[80:81], v12, v86
	v_cvt_scalef32_pk_f32_fp4 v[82:83], v12, v86 op_sel:[1,0,0]
	v_pk_mul_f32 v[84:85], v[80:81], v[132:133]
	v_cvt_scalef32_pk_f32_fp4 v[80:81], v12, v86 op_sel:[0,1,0]
	v_pk_fma_f32 v[84:85], v[82:83], v[130:131], v[84:85]
	v_cvt_scalef32_pk_f32_fp4 v[82:83], v12, v86 op_sel:[1,1,0]
	v_pk_fma_f32 v[84:85], v[80:81], v[128:129], v[84:85]
	v_cvt_scalef32_pk_f32_fp4 v[80:81], v13, v86
	v_pk_fma_f32 v[84:85], v[82:83], v[126:127], v[84:85]
	v_cvt_scalef32_pk_f32_fp4 v[82:83], v13, v86 op_sel:[1,0,0]
	v_pk_fma_f32 v[84:85], v[80:81], v[124:125], v[84:85]
	v_cvt_scalef32_pk_f32_fp4 v[80:81], v13, v86 op_sel:[0,1,0]
	v_pk_fma_f32 v[84:85], v[82:83], v[122:123], v[84:85]
	v_cvt_scalef32_pk_f32_fp4 v[82:83], v13, v86 op_sel:[1,1,0]
	v_pk_fma_f32 v[84:85], v[80:81], v[120:121], v[84:85]
	v_cvt_scalef32_pk_f32_fp4 v[80:81], v14, v86
	v_pk_fma_f32 v[84:85], v[82:83], v[118:119], v[84:85]
	v_cvt_scalef32_pk_f32_fp4 v[82:83], v14, v86 op_sel:[1,0,0]
	v_pk_fma_f32 v[84:85], v[80:81], v[116:117], v[84:85]
	v_cvt_scalef32_pk_f32_fp4 v[80:81], v14, v86 op_sel:[0,1,0]
	v_pk_fma_f32 v[84:85], v[82:83], v[114:115], v[84:85]
	v_cvt_scalef32_pk_f32_fp4 v[82:83], v14, v86 op_sel:[1,1,0]
	v_pk_fma_f32 v[84:85], v[80:81], v[112:113], v[84:85]
	v_cvt_scalef32_pk_f32_fp4 v[80:81], v15, v86
	v_pk_fma_f32 v[84:85], v[82:83], v[110:111], v[84:85]
	v_cvt_scalef32_pk_f32_fp4 v[82:83], v15, v86 op_sel:[1,0,0]
	v_pk_fma_f32 v[84:85], v[80:81], v[106:107], v[84:85]
	v_cvt_scalef32_pk_f32_fp4 v[80:81], v15, v86 op_sel:[0,1,0]
	v_pk_fma_f32 v[84:85], v[82:83], v[108:109], v[84:85]
	v_cvt_scalef32_pk_f32_fp4 v[82:83], v15, v86 op_sel:[1,1,0]
	v_pk_fma_f32 v[84:85], v[80:81], v[104:105], v[84:85]
	v_pk_fma_f32 v[84:85], v[82:83], v[102:103], v[84:85]
	v_add_f32_e32 v174, v84, v85
	v_lshl_add_u32 v87, s5, 10, v196
	v_lshl_add_u32 v88, s5, 7, v92
	global_load_dwordx4 v[12:15], v87, s[12:13] sc1
	global_load_ubyte v67, v88, s[14:15]
	s_waitcnt vmcnt(30)
	v_lshlrev_b32_e32 v86, 23, v68
	v_cvt_scalef32_pk_f32_fp4 v[80:81], v16, v86
	v_cvt_scalef32_pk_f32_fp4 v[82:83], v16, v86 op_sel:[1,0,0]
	v_pk_mul_f32 v[84:85], v[80:81], v[132:133]
	v_cvt_scalef32_pk_f32_fp4 v[80:81], v16, v86 op_sel:[0,1,0]
	v_pk_fma_f32 v[84:85], v[82:83], v[130:131], v[84:85]
	v_cvt_scalef32_pk_f32_fp4 v[82:83], v16, v86 op_sel:[1,1,0]
	v_pk_fma_f32 v[84:85], v[80:81], v[128:129], v[84:85]
	v_cvt_scalef32_pk_f32_fp4 v[80:81], v17, v86
	v_pk_fma_f32 v[84:85], v[82:83], v[126:127], v[84:85]
	v_cvt_scalef32_pk_f32_fp4 v[82:83], v17, v86 op_sel:[1,0,0]
	v_pk_fma_f32 v[84:85], v[80:81], v[124:125], v[84:85]
	v_cvt_scalef32_pk_f32_fp4 v[80:81], v17, v86 op_sel:[0,1,0]
	v_pk_fma_f32 v[84:85], v[82:83], v[122:123], v[84:85]
	v_cvt_scalef32_pk_f32_fp4 v[82:83], v17, v86 op_sel:[1,1,0]
	v_pk_fma_f32 v[84:85], v[80:81], v[120:121], v[84:85]
	v_cvt_scalef32_pk_f32_fp4 v[80:81], v18, v86
	v_pk_fma_f32 v[84:85], v[82:83], v[118:119], v[84:85]
	v_cvt_scalef32_pk_f32_fp4 v[82:83], v18, v86 op_sel:[1,0,0]
	v_pk_fma_f32 v[84:85], v[80:81], v[116:117], v[84:85]
	v_cvt_scalef32_pk_f32_fp4 v[80:81], v18, v86 op_sel:[0,1,0]
	v_pk_fma_f32 v[84:85], v[82:83], v[114:115], v[84:85]
	v_cvt_scalef32_pk_f32_fp4 v[82:83], v18, v86 op_sel:[1,1,0]
	v_pk_fma_f32 v[84:85], v[80:81], v[112:113], v[84:85]
	v_cvt_scalef32_pk_f32_fp4 v[80:81], v19, v86
	v_pk_fma_f32 v[84:85], v[82:83], v[110:111], v[84:85]
	v_cvt_scalef32_pk_f32_fp4 v[82:83], v19, v86 op_sel:[1,0,0]
	v_pk_fma_f32 v[84:85], v[80:81], v[106:107], v[84:85]
	v_cvt_scalef32_pk_f32_fp4 v[80:81], v19, v86 op_sel:[0,1,0]
	v_pk_fma_f32 v[84:85], v[82:83], v[108:109], v[84:85]
	v_cvt_scalef32_pk_f32_fp4 v[82:83], v19, v86 op_sel:[1,1,0]
	v_pk_fma_f32 v[84:85], v[80:81], v[104:105], v[84:85]
	v_pk_fma_f32 v[84:85], v[82:83], v[102:103], v[84:85]
	v_add_f32_e32 v175, v84, v85
	v_lshl_add_u32 v87, s6, 10, v196
	v_lshl_add_u32 v88, s6, 7, v92
	global_load_dwordx4 v[16:19], v87, s[12:13] sc1
	global_load_ubyte v68, v88, s[14:15]
	s_waitcnt vmcnt(30)
	v_lshlrev_b32_e32 v86, 23, v69
	v_cvt_scalef32_pk_f32_fp4 v[80:81], v20, v86
	v_cvt_scalef32_pk_f32_fp4 v[82:83], v20, v86 op_sel:[1,0,0]
	v_pk_mul_f32 v[84:85], v[80:81], v[132:133]
	v_cvt_scalef32_pk_f32_fp4 v[80:81], v20, v86 op_sel:[0,1,0]
	v_pk_fma_f32 v[84:85], v[82:83], v[130:131], v[84:85]
	v_cvt_scalef32_pk_f32_fp4 v[82:83], v20, v86 op_sel:[1,1,0]
	v_pk_fma_f32 v[84:85], v[80:81], v[128:129], v[84:85]
	v_cvt_scalef32_pk_f32_fp4 v[80:81], v21, v86
	v_pk_fma_f32 v[84:85], v[82:83], v[126:127], v[84:85]
	v_cvt_scalef32_pk_f32_fp4 v[82:83], v21, v86 op_sel:[1,0,0]
	v_pk_fma_f32 v[84:85], v[80:81], v[124:125], v[84:85]
	v_cvt_scalef32_pk_f32_fp4 v[80:81], v21, v86 op_sel:[0,1,0]
	v_pk_fma_f32 v[84:85], v[82:83], v[122:123], v[84:85]
	v_cvt_scalef32_pk_f32_fp4 v[82:83], v21, v86 op_sel:[1,1,0]
	v_pk_fma_f32 v[84:85], v[80:81], v[120:121], v[84:85]
	v_cvt_scalef32_pk_f32_fp4 v[80:81], v22, v86
	v_pk_fma_f32 v[84:85], v[82:83], v[118:119], v[84:85]
	v_cvt_scalef32_pk_f32_fp4 v[82:83], v22, v86 op_sel:[1,0,0]
	v_pk_fma_f32 v[84:85], v[80:81], v[116:117], v[84:85]
	v_cvt_scalef32_pk_f32_fp4 v[80:81], v22, v86 op_sel:[0,1,0]
	v_pk_fma_f32 v[84:85], v[82:83], v[114:115], v[84:85]
	v_cvt_scalef32_pk_f32_fp4 v[82:83], v22, v86 op_sel:[1,1,0]
	v_pk_fma_f32 v[84:85], v[80:81], v[112:113], v[84:85]
	v_cvt_scalef32_pk_f32_fp4 v[80:81], v23, v86
	v_pk_fma_f32 v[84:85], v[82:83], v[110:111], v[84:85]
	v_cvt_scalef32_pk_f32_fp4 v[82:83], v23, v86 op_sel:[1,0,0]
	v_pk_fma_f32 v[84:85], v[80:81], v[106:107], v[84:85]
	v_cvt_scalef32_pk_f32_fp4 v[80:81], v23, v86 op_sel:[0,1,0]
	v_pk_fma_f32 v[84:85], v[82:83], v[108:109], v[84:85]
	v_cvt_scalef32_pk_f32_fp4 v[82:83], v23, v86 op_sel:[1,1,0]
	v_pk_fma_f32 v[84:85], v[80:81], v[104:105], v[84:85]
	v_pk_fma_f32 v[84:85], v[82:83], v[102:103], v[84:85]
	v_add_f32_e32 v176, v84, v85
	v_lshl_add_u32 v87, s7, 10, v196
	v_lshl_add_u32 v88, s7, 7, v92
	global_load_dwordx4 v[20:23], v87, s[12:13] sc1
	global_load_ubyte v69, v88, s[14:15]
	s_waitcnt vmcnt(30)
; __device__ __forceinline__ float gelu_tanh(float x) { const float u = 0.7978845608028654f * (x + 0.044715f * x * x * x); const float e = __expf(2.0f * u); return 0.5f * x * (2.0f - 2.0f * frcp(e + 1.0f)); }
; __device__ __forceinline__ void peer_gather(const Frame& F, int l) {
;     ...
;                 if (k < 4) {
;                     f32x2 d2 = (f32x2){0.f, 0.f};
; #pragma unroll
;                     for (int i = 0; i < 4; ++i) { const unsigned w = rr[s][i];
;                         d2 += xp[4 * i + 0] * __builtin_amdgcn_cvt_scalef32_pk_f32_fp4(w, bsc, 0); d2 += xp[4 * i + 1] * __builtin_amdgcn_cvt_scalef32_pk_f32_fp4(w, bsc, 1);
;                         d2 += xp[4 * i + 2] * __builtin_amdgcn_cvt_scalef32_pk_f32_fp4(w, bsc, 2); d2 += xp[4 * i + 3] * __builtin_amdgcn_cvt_scalef32_pk_f32_fp4(w, bsc, 3); }
;                     const float act = wave_sum_dpp(d2[0] + d2[1]);
;                     const int idx = eb + 4 * g + k;
;                     const float gwt = __uint_as_float(idx < 64 ? __builtin_amdgcn_readlane(__float_as_uint(w0), idx) : __builtin_amdgcn_readlane(__float_as_uint(w1), idx - 64));
;                     cf[k] = gwt * gelu_tanh(act);
	v_lshlrev_b32_e32 v86, 23, v70
	v_cvt_scalef32_pk_f32_fp4 v[80:81], v24, v86
	v_cvt_scalef32_pk_f32_fp4 v[82:83], v24, v86 op_sel:[1,0,0]
	v_pk_mul_f32 v[84:85], v[80:81], v[132:133]
	v_cvt_scalef32_pk_f32_fp4 v[80:81], v24, v86 op_sel:[0,1,0]
	v_pk_fma_f32 v[84:85], v[82:83], v[130:131], v[84:85]
	v_cvt_scalef32_pk_f32_fp4 v[82:83], v24, v86 op_sel:[1,1,0]
	v_pk_fma_f32 v[84:85], v[80:81], v[128:129], v[84:85]
	v_cvt_scalef32_pk_f32_fp4 v[80:81], v25, v86
	v_pk_fma_f32 v[84:85], v[82:83], v[126:127], v[84:85]
	v_cvt_scalef32_pk_f32_fp4 v[82:83], v25, v86 op_sel:[1,0,0]
	v_pk_fma_f32 v[84:85], v[80:81], v[124:125], v[84:85]
	v_cvt_scalef32_pk_f32_fp4 v[80:81], v25, v86 op_sel:[0,1,0]
	v_pk_fma_f32 v[84:85], v[82:83], v[122:123], v[84:85]
	v_cvt_scalef32_pk_f32_fp4 v[82:83], v25, v86 op_sel:[1,1,0]
	v_pk_fma_f32 v[84:85], v[80:81], v[120:121], v[84:85]
	v_cvt_scalef32_pk_f32_fp4 v[80:81], v26, v86
	v_pk_fma_f32 v[84:85], v[82:83], v[118:119], v[84:85]
	v_cvt_scalef32_pk_f32_fp4 v[82:83], v26, v86 op_sel:[1,0,0]
	v_pk_fma_f32 v[84:85], v[80:81], v[116:117], v[84:85]
	v_cvt_scalef32_pk_f32_fp4 v[80:81], v26, v86 op_sel:[0,1,0]
	v_pk_fma_f32 v[84:85], v[82:83], v[114:115], v[84:85]
	v_cvt_scalef32_pk_f32_fp4 v[82:83], v26, v86 op_sel:[1,1,0]
	v_pk_fma_f32 v[84:85], v[80:81], v[112:113], v[84:85]
	v_cvt_scalef32_pk_f32_fp4 v[80:81], v27, v86
	v_pk_fma_f32 v[84:85], v[82:83], v[110:111], v[84:85]
	v_cvt_scalef32_pk_f32_fp4 v[82:83], v27, v86 op_sel:[1,0,0]
	v_pk_fma_f32 v[84:85], v[80:81], v[106:107], v[84:85]
	v_cvt_scalef32_pk_f32_fp4 v[80:81], v27, v86 op_sel:[0,1,0]
	v_pk_fma_f32 v[84:85], v[82:83], v[108:109], v[84:85]
	v_cvt_scalef32_pk_f32_fp4 v[82:83], v27, v86 op_sel:[1,1,0]
	v_pk_fma_f32 v[84:85], v[80:81], v[104:105], v[84:85]
	v_pk_fma_f32 v[84:85], v[82:83], v[102:103], v[84:85]
	v_add_f32_e32 v177, v84, v85
	v_lshl_add_u32 v87, s58, 10, v196
	v_lshl_add_u32 v88, s58, 7, v92
	global_load_dwordx4 v[24:27], v87, s[12:13] sc1
	global_load_ubyte v70, v88, s[14:15]
	s_waitcnt vmcnt(30)
	v_lshlrev_b32_e32 v86, 23, v71
	v_cvt_scalef32_pk_f32_fp4 v[80:81], v28, v86
	v_cvt_scalef32_pk_f32_fp4 v[82:83], v28, v86 op_sel:[1,0,0]
	v_pk_mul_f32 v[84:85], v[80:81], v[132:133]
	v_cvt_scalef32_pk_f32_fp4 v[80:81], v28, v86 op_sel:[0,1,0]
	v_pk_fma_f32 v[84:85], v[82:83], v[130:131], v[84:85]
	v_cvt_scalef32_pk_f32_fp4 v[82:83], v28, v86 op_sel:[1,1,0]
	v_pk_fma_f32 v[84:85], v[80:81], v[128:129], v[84:85]
	v_cvt_scalef32_pk_f32_fp4 v[80:81], v29, v86
	v_pk_fma_f32 v[84:85], v[82:83], v[126:127], v[84:85]
	v_cvt_scalef32_pk_f32_fp4 v[82:83], v29, v86 op_sel:[1,0,0]
	v_pk_fma_f32 v[84:85], v[80:81], v[124:125], v[84:85]
	v_cvt_scalef32_pk_f32_fp4 v[80:81], v29, v86 op_sel:[0,1,0]
	v_pk_fma_f32 v[84:85], v[82:83], v[122:123], v[84:85]
	v_cvt_scalef32_pk_f32_fp4 v[82:83], v29, v86 op_sel:[1,1,0]
	v_pk_fma_f32 v[84:85], v[80:81], v[120:121], v[84:85]
	v_cvt_scalef32_pk_f32_fp4 v[80:81], v30, v86
	v_pk_fma_f32 v[84:85], v[82:83], v[118:119], v[84:85]
	v_cvt_scalef32_pk_f32_fp4 v[82:83], v30, v86 op_sel:[1,0,0]
	v_pk_fma_f32 v[84:85], v[80:81], v[116:117], v[84:85]
	v_cvt_scalef32_pk_f32_fp4 v[80:81], v30, v86 op_sel:[0,1,0]
	v_pk_fma_f32 v[84:85], v[82:83], v[114:115], v[84:85]
	v_cvt_scalef32_pk_f32_fp4 v[82:83], v30, v86 op_sel:[1,1,0]
	v_pk_fma_f32 v[84:85], v[80:81], v[112:113], v[84:85]
	v_cvt_scalef32_pk_f32_fp4 v[80:81], v31, v86
	v_pk_fma_f32 v[84:85], v[82:83], v[110:111], v[84:85]
	v_cvt_scalef32_pk_f32_fp4 v[82:83], v31, v86 op_sel:[1,0,0]
	v_pk_fma_f32 v[84:85], v[80:81], v[106:107], v[84:85]
	v_cvt_scalef32_pk_f32_fp4 v[80:81], v31, v86 op_sel:[0,1,0]
	v_pk_fma_f32 v[84:85], v[82:83], v[108:109], v[84:85]
	v_cvt_scalef32_pk_f32_fp4 v[82:83], v31, v86 op_sel:[1,1,0]
	v_pk_fma_f32 v[84:85], v[80:81], v[104:105], v[84:85]
	v_pk_fma_f32 v[84:85], v[82:83], v[102:103], v[84:85]
	v_add_f32_e32 v178, v84, v85
	v_lshl_add_u32 v87, s59, 10, v196
	v_lshl_add_u32 v88, s59, 7, v92
	global_load_dwordx4 v[28:31], v87, s[12:13] sc1
	global_load_ubyte v71, v88, s[14:15]
	v_add_f32_dpp v179, v171, v171 quad_perm:[1,0,3,2] row_mask:0xf bank_mask:0xf
	v_add_f32_dpp v180, v172, v172 quad_perm:[1,0,3,2] row_mask:0xf bank_mask:0xf
	v_cndmask_b32_e64 v181, v179, v180, vcc
	v_add_f32_dpp v179, v173, v173 quad_perm:[1,0,3,2] row_mask:0xf bank_mask:0xf
	v_add_f32_dpp v180, v174, v174 quad_perm:[1,0,3,2] row_mask:0xf bank_mask:0xf
	v_cndmask_b32_e64 v182, v179, v180, vcc
	v_add_f32_dpp v179, v175, v175 quad_perm:[1,0,3,2] row_mask:0xf bank_mask:0xf
	v_add_f32_dpp v180, v176, v176 quad_perm:[1,0,3,2] row_mask:0xf bank_mask:0xf
	v_cndmask_b32_e64 v183, v179, v180, vcc
	v_add_f32_dpp v179, v177, v177 quad_perm:[1,0,3,2] row_mask:0xf bank_mask:0xf
	v_add_f32_dpp v180, v178, v178 quad_perm:[1,0,3,2] row_mask:0xf bank_mask:0xf
	v_cndmask_b32_e64 v184, v179, v180, vcc
	v_add_f32_dpp v179, v181, v181 quad_perm:[2,3,0,1] row_mask:0xf bank_mask:0xf
	v_add_f32_dpp v180, v182, v182 quad_perm:[2,3,0,1] row_mask:0xf bank_mask:0xf
	v_cndmask_b32_e64 v185, v179, v180, s[100:101]
	v_add_f32_dpp v179, v183, v183 quad_perm:[2,3,0,1] row_mask:0xf bank_mask:0xf
	v_add_f32_dpp v180, v184, v184 quad_perm:[2,3,0,1] row_mask:0xf bank_mask:0xf
	v_cndmask_b32_e64 v186, v179, v180, s[100:101]
	s_nop 0
	v_add_f32_dpp v187, v185, v185 row_shl:4 row_mask:0xf bank_mask:0x5
	v_add_f32_dpp v187, v186, v186 row_shr:4 row_mask:0xf bank_mask:0xa
	s_nop 1
	v_add_f32_dpp v188, v187, v187 row_ror:8 row_mask:0xf bank_mask:0xf
	v_mov_b32_e32 v189, v188
	s_nop 1
	v_permlane16_swap_b32 v189, v188
	v_add_f32_e32 v188, v188, v189
	v_mov_b32_e32 v189, v188
	s_nop 1
	v_permlane32_swap_b32 v189, v188
	v_add_f32_e32 v188, v188, v189
	v_mul_f32_e32 v179, v188, v240
	v_mul_f32_e32 v179, v188, v179
	v_fma_f32 v179, v188, v179, v188
	v_mul_f32_e32 v179, 0x3f4c422a, v179
	v_add_f32_e32 v179, v179, v179
	v_mul_f32_e32 v179, 0x3fb8aa3b, v179
	v_exp_f32_e32 v179, v179
	v_mul_f32_e32 v180, 0.5, v188
	v_add_f32_e32 v179, 1.0, v179
	v_rcp_f32_e32 v179, v179
	s_nop 0
	v_fma_f32 v179, v179, -2.0, 2.0
	v_mul_f32_e32 v179, v180, v179
	v_mul_f32_e32 v181, v193, v179
	s_nop 0
	v_readlane_b32 s42, v181, 0
	v_readlane_b32 s44, v181, 1
	v_readlane_b32 s46, v181, 2
	v_readlane_b32 s48, v181, 3
	v_readlane_b32 s50, v181, 4
	v_readlane_b32 s52, v181, 5
	v_readlane_b32 s54, v181, 6
	v_readlane_b32 s56, v181, 7
	s_waitcnt vmcnt(30)
; __device__ __forceinline__ void peer_gather(const Frame& F, int l) {
;     ...
;                 } else {
;                     const float c1 = cf[k - 4];
; #pragma unroll
;                     for (int i = 0; i < 4; ++i) { const unsigned w = rr[s][i];
;                         acc[4 * i + 0] += __builtin_amdgcn_cvt_scalef32_pk_f32_fp4(w, bsc, 0) * c1; acc[4 * i + 1] += __builtin_amdgcn_cvt_scalef32_pk_f32_fp4(w, bsc, 1) * c1;
;                         acc[4 * i + 2] += __builtin_amdgcn_cvt_scalef32_pk_f32_fp4(w, bsc, 2) * c1; acc[4 * i + 3] += __builtin_amdgcn_cvt_scalef32_pk_f32_fp4(w, bsc, 3) * c1; }
;                 }
	v_lshlrev_b32_e32 v86, 23, v72
	v_cvt_scalef32_pk_f32_fp4 v[80:81], v32, v86
	v_cvt_scalef32_pk_f32_fp4 v[82:83], v32, v86 op_sel:[1,0,0]
	v_pk_fma_f32 v[164:165], v[80:81], s[42:43], v[164:165] op_sel_hi:[1,0,1]
	v_cvt_scalef32_pk_f32_fp4 v[80:81], v32, v86 op_sel:[0,1,0]
	v_pk_fma_f32 v[162:163], v[82:83], s[42:43], v[162:163] op_sel_hi:[1,0,1]
	v_cvt_scalef32_pk_f32_fp4 v[82:83], v32, v86 op_sel:[1,1,0]
	v_pk_fma_f32 v[160:161], v[80:81], s[42:43], v[160:161] op_sel_hi:[1,0,1]
	v_cvt_scalef32_pk_f32_fp4 v[80:81], v33, v86
	v_pk_fma_f32 v[158:159], v[82:83], s[42:43], v[158:159] op_sel_hi:[1,0,1]
	v_cvt_scalef32_pk_f32_fp4 v[82:83], v33, v86 op_sel:[1,0,0]
	v_pk_fma_f32 v[156:157], v[80:81], s[42:43], v[156:157] op_sel_hi:[1,0,1]
	v_cvt_scalef32_pk_f32_fp4 v[80:81], v33, v86 op_sel:[0,1,0]
	v_pk_fma_f32 v[154:155], v[82:83], s[42:43], v[154:155] op_sel_hi:[1,0,1]
	v_cvt_scalef32_pk_f32_fp4 v[82:83], v33, v86 op_sel:[1,1,0]
	v_pk_fma_f32 v[152:153], v[80:81], s[42:43], v[152:153] op_sel_hi:[1,0,1]
	v_cvt_scalef32_pk_f32_fp4 v[80:81], v34, v86
	v_pk_fma_f32 v[150:151], v[82:83], s[42:43], v[150:151] op_sel_hi:[1,0,1]
	v_cvt_scalef32_pk_f32_fp4 v[82:83], v34, v86 op_sel:[1,0,0]
	v_pk_fma_f32 v[148:149], v[80:81], s[42:43], v[148:149] op_sel_hi:[1,0,1]
	v_cvt_scalef32_pk_f32_fp4 v[80:81], v34, v86 op_sel:[0,1,0]
	v_pk_fma_f32 v[146:147], v[82:83], s[42:43], v[146:147] op_sel_hi:[1,0,1]
	v_cvt_scalef32_pk_f32_fp4 v[82:83], v34, v86 op_sel:[1,1,0]
	v_pk_fma_f32 v[144:145], v[80:81], s[42:43], v[144:145] op_sel_hi:[1,0,1]
	v_cvt_scalef32_pk_f32_fp4 v[80:81], v35, v86
	v_pk_fma_f32 v[142:143], v[82:83], s[42:43], v[142:143] op_sel_hi:[1,0,1]
	v_cvt_scalef32_pk_f32_fp4 v[82:83], v35, v86 op_sel:[1,0,0]
	v_pk_fma_f32 v[140:141], v[80:81], s[42:43], v[140:141] op_sel_hi:[1,0,1]
	v_cvt_scalef32_pk_f32_fp4 v[80:81], v35, v86 op_sel:[0,1,0]
	v_pk_fma_f32 v[138:139], v[82:83], s[42:43], v[138:139] op_sel_hi:[1,0,1]
	v_cvt_scalef32_pk_f32_fp4 v[82:83], v35, v86 op_sel:[1,1,0]
	v_pk_fma_f32 v[136:137], v[80:81], s[42:43], v[136:137] op_sel_hi:[1,0,1]
	v_pk_fma_f32 v[134:135], v[82:83], s[42:43], v[134:135] op_sel_hi:[1,0,1]
	v_lshl_add_u32 v87, s0, 10, v196
	v_lshl_add_u32 v88, s0, 7, v92
	global_load_dwordx4 v[32:35], v87, s[16:17] sc1
	global_load_ubyte v72, v88, s[14:15] offset:64
	s_waitcnt vmcnt(30)
	v_lshlrev_b32_e32 v86, 23, v73
	v_cvt_scalef32_pk_f32_fp4 v[80:81], v36, v86
	v_cvt_scalef32_pk_f32_fp4 v[82:83], v36, v86 op_sel:[1,0,0]
	v_pk_fma_f32 v[164:165], v[80:81], s[44:45], v[164:165] op_sel_hi:[1,0,1]
	v_cvt_scalef32_pk_f32_fp4 v[80:81], v36, v86 op_sel:[0,1,0]
	v_pk_fma_f32 v[162:163], v[82:83], s[44:45], v[162:163] op_sel_hi:[1,0,1]
	v_cvt_scalef32_pk_f32_fp4 v[82:83], v36, v86 op_sel:[1,1,0]
	v_pk_fma_f32 v[160:161], v[80:81], s[44:45], v[160:161] op_sel_hi:[1,0,1]
	v_cvt_scalef32_pk_f32_fp4 v[80:81], v37, v86
	v_pk_fma_f32 v[158:159], v[82:83], s[44:45], v[158:159] op_sel_hi:[1,0,1]
	v_cvt_scalef32_pk_f32_fp4 v[82:83], v37, v86 op_sel:[1,0,0]
	v_pk_fma_f32 v[156:157], v[80:81], s[44:45], v[156:157] op_sel_hi:[1,0,1]
	v_cvt_scalef32_pk_f32_fp4 v[80:81], v37, v86 op_sel:[0,1,0]
	v_pk_fma_f32 v[154:155], v[82:83], s[44:45], v[154:155] op_sel_hi:[1,0,1]
	v_cvt_scalef32_pk_f32_fp4 v[82:83], v37, v86 op_sel:[1,1,0]
	v_pk_fma_f32 v[152:153], v[80:81], s[44:45], v[152:153] op_sel_hi:[1,0,1]
	v_cvt_scalef32_pk_f32_fp4 v[80:81], v38, v86
	v_pk_fma_f32 v[150:151], v[82:83], s[44:45], v[150:151] op_sel_hi:[1,0,1]
	v_cvt_scalef32_pk_f32_fp4 v[82:83], v38, v86 op_sel:[1,0,0]
	v_pk_fma_f32 v[148:149], v[80:81], s[44:45], v[148:149] op_sel_hi:[1,0,1]
	v_cvt_scalef32_pk_f32_fp4 v[80:81], v38, v86 op_sel:[0,1,0]
	v_pk_fma_f32 v[146:147], v[82:83], s[44:45], v[146:147] op_sel_hi:[1,0,1]
	v_cvt_scalef32_pk_f32_fp4 v[82:83], v38, v86 op_sel:[1,1,0]
	v_pk_fma_f32 v[144:145], v[80:81], s[44:45], v[144:145] op_sel_hi:[1,0,1]
	v_cvt_scalef32_pk_f32_fp4 v[80:81], v39, v86
	v_pk_fma_f32 v[142:143], v[82:83], s[44:45], v[142:143] op_sel_hi:[1,0,1]
	v_cvt_scalef32_pk_f32_fp4 v[82:83], v39, v86 op_sel:[1,0,0]
	v_pk_fma_f32 v[140:141], v[80:81], s[44:45], v[140:141] op_sel_hi:[1,0,1]
	v_cvt_scalef32_pk_f32_fp4 v[80:81], v39, v86 op_sel:[0,1,0]
	v_pk_fma_f32 v[138:139], v[82:83], s[44:45], v[138:139] op_sel_hi:[1,0,1]
	v_cvt_scalef32_pk_f32_fp4 v[82:83], v39, v86 op_sel:[1,1,0]
	v_pk_fma_f32 v[136:137], v[80:81], s[44:45], v[136:137] op_sel_hi:[1,0,1]
	v_pk_fma_f32 v[134:135], v[82:83], s[44:45], v[134:135] op_sel_hi:[1,0,1]
	v_lshl_add_u32 v87, s1, 10, v196
	v_lshl_add_u32 v88, s1, 7, v92
	global_load_dwordx4 v[36:39], v87, s[16:17] sc1
	global_load_ubyte v73, v88, s[14:15] offset:64
	s_waitcnt vmcnt(30)
; __device__ __forceinline__ void peer_gather(const Frame& F, int l) {
;     ...
;                 } else {
;                     const float c1 = cf[k - 4];
; #pragma unroll
;                     for (int i = 0; i < 4; ++i) { const unsigned w = rr[s][i];
;                         acc[4 * i + 0] += __builtin_amdgcn_cvt_scalef32_pk_f32_fp4(w, bsc, 0) * c1; acc[4 * i + 1] += __builtin_amdgcn_cvt_scalef32_pk_f32_fp4(w, bsc, 1) * c1;
;                         acc[4 * i + 2] += __builtin_amdgcn_cvt_scalef32_pk_f32_fp4(w, bsc, 2) * c1; acc[4 * i + 3] += __builtin_amdgcn_cvt_scalef32_pk_f32_fp4(w, bsc, 3) * c1; }
;                 }
	v_lshlrev_b32_e32 v86, 23, v74
	v_cvt_scalef32_pk_f32_fp4 v[80:81], v40, v86
	v_cvt_scalef32_pk_f32_fp4 v[82:83], v40, v86 op_sel:[1,0,0]
	v_pk_fma_f32 v[164:165], v[80:81], s[46:47], v[164:165] op_sel_hi:[1,0,1]
	v_cvt_scalef32_pk_f32_fp4 v[80:81], v40, v86 op_sel:[0,1,0]
	v_pk_fma_f32 v[162:163], v[82:83], s[46:47], v[162:163] op_sel_hi:[1,0,1]
	v_cvt_scalef32_pk_f32_fp4 v[82:83], v40, v86 op_sel:[1,1,0]
	v_pk_fma_f32 v[160:161], v[80:81], s[46:47], v[160:161] op_sel_hi:[1,0,1]
	v_cvt_scalef32_pk_f32_fp4 v[80:81], v41, v86
	v_pk_fma_f32 v[158:159], v[82:83], s[46:47], v[158:159] op_sel_hi:[1,0,1]
	v_cvt_scalef32_pk_f32_fp4 v[82:83], v41, v86 op_sel:[1,0,0]
	v_pk_fma_f32 v[156:157], v[80:81], s[46:47], v[156:157] op_sel_hi:[1,0,1]
	v_cvt_scalef32_pk_f32_fp4 v[80:81], v41, v86 op_sel:[0,1,0]
	v_pk_fma_f32 v[154:155], v[82:83], s[46:47], v[154:155] op_sel_hi:[1,0,1]
	v_cvt_scalef32_pk_f32_fp4 v[82:83], v41, v86 op_sel:[1,1,0]
	v_pk_fma_f32 v[152:153], v[80:81], s[46:47], v[152:153] op_sel_hi:[1,0,1]
	v_cvt_scalef32_pk_f32_fp4 v[80:81], v42, v86
	v_pk_fma_f32 v[150:151], v[82:83], s[46:47], v[150:151] op_sel_hi:[1,0,1]
	v_cvt_scalef32_pk_f32_fp4 v[82:83], v42, v86 op_sel:[1,0,0]
	v_pk_fma_f32 v[148:149], v[80:81], s[46:47], v[148:149] op_sel_hi:[1,0,1]
	v_cvt_scalef32_pk_f32_fp4 v[80:81], v42, v86 op_sel:[0,1,0]
	v_pk_fma_f32 v[146:147], v[82:83], s[46:47], v[146:147] op_sel_hi:[1,0,1]
	v_cvt_scalef32_pk_f32_fp4 v[82:83], v42, v86 op_sel:[1,1,0]
	v_pk_fma_f32 v[144:145], v[80:81], s[46:47], v[144:145] op_sel_hi:[1,0,1]
	v_cvt_scalef32_pk_f32_fp4 v[80:81], v43, v86
	v_pk_fma_f32 v[142:143], v[82:83], s[46:47], v[142:143] op_sel_hi:[1,0,1]
	v_cvt_scalef32_pk_f32_fp4 v[82:83], v43, v86 op_sel:[1,0,0]
	v_pk_fma_f32 v[140:141], v[80:81], s[46:47], v[140:141] op_sel_hi:[1,0,1]
	v_cvt_scalef32_pk_f32_fp4 v[80:81], v43, v86 op_sel:[0,1,0]
	v_pk_fma_f32 v[138:139], v[82:83], s[46:47], v[138:139] op_sel_hi:[1,0,1]
	v_cvt_scalef32_pk_f32_fp4 v[82:83], v43, v86 op_sel:[1,1,0]
	v_pk_fma_f32 v[136:137], v[80:81], s[46:47], v[136:137] op_sel_hi:[1,0,1]
	v_pk_fma_f32 v[134:135], v[82:83], s[46:47], v[134:135] op_sel_hi:[1,0,1]
	v_lshl_add_u32 v87, s4, 10, v196
	v_lshl_add_u32 v88, s4, 7, v92
	global_load_dwordx4 v[40:43], v87, s[16:17] sc1
	global_load_ubyte v74, v88, s[14:15] offset:64
	s_waitcnt vmcnt(30)
	v_lshlrev_b32_e32 v86, 23, v75
	v_cvt_scalef32_pk_f32_fp4 v[80:81], v44, v86
	v_cvt_scalef32_pk_f32_fp4 v[82:83], v44, v86 op_sel:[1,0,0]
	v_pk_fma_f32 v[164:165], v[80:81], s[48:49], v[164:165] op_sel_hi:[1,0,1]
	v_cvt_scalef32_pk_f32_fp4 v[80:81], v44, v86 op_sel:[0,1,0]
	v_pk_fma_f32 v[162:163], v[82:83], s[48:49], v[162:163] op_sel_hi:[1,0,1]
	v_cvt_scalef32_pk_f32_fp4 v[82:83], v44, v86 op_sel:[1,1,0]
	v_pk_fma_f32 v[160:161], v[80:81], s[48:49], v[160:161] op_sel_hi:[1,0,1]
	v_cvt_scalef32_pk_f32_fp4 v[80:81], v45, v86
	v_pk_fma_f32 v[158:159], v[82:83], s[48:49], v[158:159] op_sel_hi:[1,0,1]
	v_cvt_scalef32_pk_f32_fp4 v[82:83], v45, v86 op_sel:[1,0,0]
	v_pk_fma_f32 v[156:157], v[80:81], s[48:49], v[156:157] op_sel_hi:[1,0,1]
	v_cvt_scalef32_pk_f32_fp4 v[80:81], v45, v86 op_sel:[0,1,0]
	v_pk_fma_f32 v[154:155], v[82:83], s[48:49], v[154:155] op_sel_hi:[1,0,1]
	v_cvt_scalef32_pk_f32_fp4 v[82:83], v45, v86 op_sel:[1,1,0]
	v_pk_fma_f32 v[152:153], v[80:81], s[48:49], v[152:153] op_sel_hi:[1,0,1]
	v_cvt_scalef32_pk_f32_fp4 v[80:81], v46, v86
	v_pk_fma_f32 v[150:151], v[82:83], s[48:49], v[150:151] op_sel_hi:[1,0,1]
	v_cvt_scalef32_pk_f32_fp4 v[82:83], v46, v86 op_sel:[1,0,0]
	v_pk_fma_f32 v[148:149], v[80:81], s[48:49], v[148:149] op_sel_hi:[1,0,1]
	v_cvt_scalef32_pk_f32_fp4 v[80:81], v46, v86 op_sel:[0,1,0]
	v_pk_fma_f32 v[146:147], v[82:83], s[48:49], v[146:147] op_sel_hi:[1,0,1]
	v_cvt_scalef32_pk_f32_fp4 v[82:83], v46, v86 op_sel:[1,1,0]
	v_pk_fma_f32 v[144:145], v[80:81], s[48:49], v[144:145] op_sel_hi:[1,0,1]
	v_cvt_scalef32_pk_f32_fp4 v[80:81], v47, v86
	v_pk_fma_f32 v[142:143], v[82:83], s[48:49], v[142:143] op_sel_hi:[1,0,1]
	v_cvt_scalef32_pk_f32_fp4 v[82:83], v47, v86 op_sel:[1,0,0]
	v_pk_fma_f32 v[140:141], v[80:81], s[48:49], v[140:141] op_sel_hi:[1,0,1]
	v_cvt_scalef32_pk_f32_fp4 v[80:81], v47, v86 op_sel:[0,1,0]
	v_pk_fma_f32 v[138:139], v[82:83], s[48:49], v[138:139] op_sel_hi:[1,0,1]
	v_cvt_scalef32_pk_f32_fp4 v[82:83], v47, v86 op_sel:[1,1,0]
	v_pk_fma_f32 v[136:137], v[80:81], s[48:49], v[136:137] op_sel_hi:[1,0,1]
	v_pk_fma_f32 v[134:135], v[82:83], s[48:49], v[134:135] op_sel_hi:[1,0,1]
	v_lshl_add_u32 v87, s5, 10, v196
	v_lshl_add_u32 v88, s5, 7, v92
	global_load_dwordx4 v[44:47], v87, s[16:17] sc1
	global_load_ubyte v75, v88, s[14:15] offset:64
	s_waitcnt vmcnt(30)
; __device__ __forceinline__ void peer_gather(const Frame& F, int l) {
;     ...
;                 } else {
;                     const float c1 = cf[k - 4];
; #pragma unroll
;                     for (int i = 0; i < 4; ++i) { const unsigned w = rr[s][i];
;                         acc[4 * i + 0] += __builtin_amdgcn_cvt_scalef32_pk_f32_fp4(w, bsc, 0) * c1; acc[4 * i + 1] += __builtin_amdgcn_cvt_scalef32_pk_f32_fp4(w, bsc, 1) * c1;
;                         acc[4 * i + 2] += __builtin_amdgcn_cvt_scalef32_pk_f32_fp4(w, bsc, 2) * c1; acc[4 * i + 3] += __builtin_amdgcn_cvt_scalef32_pk_f32_fp4(w, bsc, 3) * c1; }
;                 }
	v_lshlrev_b32_e32 v86, 23, v76
	v_cvt_scalef32_pk_f32_fp4 v[80:81], v48, v86
	v_cvt_scalef32_pk_f32_fp4 v[82:83], v48, v86 op_sel:[1,0,0]
	v_pk_fma_f32 v[164:165], v[80:81], s[50:51], v[164:165] op_sel_hi:[1,0,1]
	v_cvt_scalef32_pk_f32_fp4 v[80:81], v48, v86 op_sel:[0,1,0]
	v_pk_fma_f32 v[162:163], v[82:83], s[50:51], v[162:163] op_sel_hi:[1,0,1]
	v_cvt_scalef32_pk_f32_fp4 v[82:83], v48, v86 op_sel:[1,1,0]
	v_pk_fma_f32 v[160:161], v[80:81], s[50:51], v[160:161] op_sel_hi:[1,0,1]
	v_cvt_scalef32_pk_f32_fp4 v[80:81], v49, v86
	v_pk_fma_f32 v[158:159], v[82:83], s[50:51], v[158:159] op_sel_hi:[1,0,1]
	v_cvt_scalef32_pk_f32_fp4 v[82:83], v49, v86 op_sel:[1,0,0]
	v_pk_fma_f32 v[156:157], v[80:81], s[50:51], v[156:157] op_sel_hi:[1,0,1]
	v_cvt_scalef32_pk_f32_fp4 v[80:81], v49, v86 op_sel:[0,1,0]
	v_pk_fma_f32 v[154:155], v[82:83], s[50:51], v[154:155] op_sel_hi:[1,0,1]
	v_cvt_scalef32_pk_f32_fp4 v[82:83], v49, v86 op_sel:[1,1,0]
	v_pk_fma_f32 v[152:153], v[80:81], s[50:51], v[152:153] op_sel_hi:[1,0,1]
	v_cvt_scalef32_pk_f32_fp4 v[80:81], v50, v86
	v_pk_fma_f32 v[150:151], v[82:83], s[50:51], v[150:151] op_sel_hi:[1,0,1]
	v_cvt_scalef32_pk_f32_fp4 v[82:83], v50, v86 op_sel:[1,0,0]
	v_pk_fma_f32 v[148:149], v[80:81], s[50:51], v[148:149] op_sel_hi:[1,0,1]
	v_cvt_scalef32_pk_f32_fp4 v[80:81], v50, v86 op_sel:[0,1,0]
	v_pk_fma_f32 v[146:147], v[82:83], s[50:51], v[146:147] op_sel_hi:[1,0,1]
	v_cvt_scalef32_pk_f32_fp4 v[82:83], v50, v86 op_sel:[1,1,0]
	v_pk_fma_f32 v[144:145], v[80:81], s[50:51], v[144:145] op_sel_hi:[1,0,1]
	v_cvt_scalef32_pk_f32_fp4 v[80:81], v51, v86
	v_pk_fma_f32 v[142:143], v[82:83], s[50:51], v[142:143] op_sel_hi:[1,0,1]
	v_cvt_scalef32_pk_f32_fp4 v[82:83], v51, v86 op_sel:[1,0,0]
	v_pk_fma_f32 v[140:141], v[80:81], s[50:51], v[140:141] op_sel_hi:[1,0,1]
	v_cvt_scalef32_pk_f32_fp4 v[80:81], v51, v86 op_sel:[0,1,0]
	v_pk_fma_f32 v[138:139], v[82:83], s[50:51], v[138:139] op_sel_hi:[1,0,1]
	v_cvt_scalef32_pk_f32_fp4 v[82:83], v51, v86 op_sel:[1,1,0]
	v_pk_fma_f32 v[136:137], v[80:81], s[50:51], v[136:137] op_sel_hi:[1,0,1]
	v_pk_fma_f32 v[134:135], v[82:83], s[50:51], v[134:135] op_sel_hi:[1,0,1]
	v_lshl_add_u32 v87, s6, 10, v196
	v_lshl_add_u32 v88, s6, 7, v92
	global_load_dwordx4 v[48:51], v87, s[16:17] sc1
	global_load_ubyte v76, v88, s[14:15] offset:64
	s_waitcnt vmcnt(30)
	v_lshlrev_b32_e32 v86, 23, v77
	v_cvt_scalef32_pk_f32_fp4 v[80:81], v52, v86
	v_cvt_scalef32_pk_f32_fp4 v[82:83], v52, v86 op_sel:[1,0,0]
	v_pk_fma_f32 v[164:165], v[80:81], s[52:53], v[164:165] op_sel_hi:[1,0,1]
	v_cvt_scalef32_pk_f32_fp4 v[80:81], v52, v86 op_sel:[0,1,0]
	v_pk_fma_f32 v[162:163], v[82:83], s[52:53], v[162:163] op_sel_hi:[1,0,1]
	v_cvt_scalef32_pk_f32_fp4 v[82:83], v52, v86 op_sel:[1,1,0]
	v_pk_fma_f32 v[160:161], v[80:81], s[52:53], v[160:161] op_sel_hi:[1,0,1]
	v_cvt_scalef32_pk_f32_fp4 v[80:81], v53, v86
	v_pk_fma_f32 v[158:159], v[82:83], s[52:53], v[158:159] op_sel_hi:[1,0,1]
	v_cvt_scalef32_pk_f32_fp4 v[82:83], v53, v86 op_sel:[1,0,0]
	v_pk_fma_f32 v[156:157], v[80:81], s[52:53], v[156:157] op_sel_hi:[1,0,1]
	v_cvt_scalef32_pk_f32_fp4 v[80:81], v53, v86 op_sel:[0,1,0]
	v_pk_fma_f32 v[154:155], v[82:83], s[52:53], v[154:155] op_sel_hi:[1,0,1]
	v_cvt_scalef32_pk_f32_fp4 v[82:83], v53, v86 op_sel:[1,1,0]
	v_pk_fma_f32 v[152:153], v[80:81], s[52:53], v[152:153] op_sel_hi:[1,0,1]
	v_cvt_scalef32_pk_f32_fp4 v[80:81], v54, v86
	v_pk_fma_f32 v[150:151], v[82:83], s[52:53], v[150:151] op_sel_hi:[1,0,1]
	v_cvt_scalef32_pk_f32_fp4 v[82:83], v54, v86 op_sel:[1,0,0]
	v_pk_fma_f32 v[148:149], v[80:81], s[52:53], v[148:149] op_sel_hi:[1,0,1]
	v_cvt_scalef32_pk_f32_fp4 v[80:81], v54, v86 op_sel:[0,1,0]
	v_pk_fma_f32 v[146:147], v[82:83], s[52:53], v[146:147] op_sel_hi:[1,0,1]
	v_cvt_scalef32_pk_f32_fp4 v[82:83], v54, v86 op_sel:[1,1,0]
	v_pk_fma_f32 v[144:145], v[80:81], s[52:53], v[144:145] op_sel_hi:[1,0,1]
	v_cvt_scalef32_pk_f32_fp4 v[80:81], v55, v86
	v_pk_fma_f32 v[142:143], v[82:83], s[52:53], v[142:143] op_sel_hi:[1,0,1]
	v_cvt_scalef32_pk_f32_fp4 v[82:83], v55, v86 op_sel:[1,0,0]
	v_pk_fma_f32 v[140:141], v[80:81], s[52:53], v[140:141] op_sel_hi:[1,0,1]
	v_cvt_scalef32_pk_f32_fp4 v[80:81], v55, v86 op_sel:[0,1,0]
	v_pk_fma_f32 v[138:139], v[82:83], s[52:53], v[138:139] op_sel_hi:[1,0,1]
	v_cvt_scalef32_pk_f32_fp4 v[82:83], v55, v86 op_sel:[1,1,0]
	v_pk_fma_f32 v[136:137], v[80:81], s[52:53], v[136:137] op_sel_hi:[1,0,1]
	v_pk_fma_f32 v[134:135], v[82:83], s[52:53], v[134:135] op_sel_hi:[1,0,1]
	v_lshl_add_u32 v87, s7, 10, v196
	v_lshl_add_u32 v88, s7, 7, v92
	global_load_dwordx4 v[52:55], v87, s[16:17] sc1
	global_load_ubyte v77, v88, s[14:15] offset:64
	s_waitcnt vmcnt(30)
; __device__ __forceinline__ void peer_gather(const Frame& F, int l) {
;     ...
;                     const float c1 = cf[k - 4];
; #pragma unroll
;                     for (int i = 0; i < 4; ++i) { const unsigned w = rr[s][i];
;                         acc[4 * i + 0] += __builtin_amdgcn_cvt_scalef32_pk_f32_fp4(w, bsc, 0) * c1; acc[4 * i + 1] += __builtin_amdgcn_cvt_scalef32_pk_f32_fp4(w, bsc, 1) * c1;
;                         acc[4 * i + 2] += __builtin_amdgcn_cvt_scalef32_pk_f32_fp4(w, bsc, 2) * c1; acc[4 * i + 3] += __builtin_amdgcn_cvt_scalef32_pk_f32_fp4(w, bsc, 3) * c1; }
	v_lshlrev_b32_e32 v86, 23, v78
	v_cvt_scalef32_pk_f32_fp4 v[80:81], v56, v86
	v_cvt_scalef32_pk_f32_fp4 v[82:83], v56, v86 op_sel:[1,0,0]
	v_pk_fma_f32 v[164:165], v[80:81], s[54:55], v[164:165] op_sel_hi:[1,0,1]
	v_cvt_scalef32_pk_f32_fp4 v[80:81], v56, v86 op_sel:[0,1,0]
	v_pk_fma_f32 v[162:163], v[82:83], s[54:55], v[162:163] op_sel_hi:[1,0,1]
	v_cvt_scalef32_pk_f32_fp4 v[82:83], v56, v86 op_sel:[1,1,0]
	v_pk_fma_f32 v[160:161], v[80:81], s[54:55], v[160:161] op_sel_hi:[1,0,1]
	v_cvt_scalef32_pk_f32_fp4 v[80:81], v57, v86
	v_pk_fma_f32 v[158:159], v[82:83], s[54:55], v[158:159] op_sel_hi:[1,0,1]
	v_cvt_scalef32_pk_f32_fp4 v[82:83], v57, v86 op_sel:[1,0,0]
	v_pk_fma_f32 v[156:157], v[80:81], s[54:55], v[156:157] op_sel_hi:[1,0,1]
	v_cvt_scalef32_pk_f32_fp4 v[80:81], v57, v86 op_sel:[0,1,0]
	v_pk_fma_f32 v[154:155], v[82:83], s[54:55], v[154:155] op_sel_hi:[1,0,1]
	v_cvt_scalef32_pk_f32_fp4 v[82:83], v57, v86 op_sel:[1,1,0]
	v_pk_fma_f32 v[152:153], v[80:81], s[54:55], v[152:153] op_sel_hi:[1,0,1]
	v_cvt_scalef32_pk_f32_fp4 v[80:81], v58, v86
	v_pk_fma_f32 v[150:151], v[82:83], s[54:55], v[150:151] op_sel_hi:[1,0,1]
	v_cvt_scalef32_pk_f32_fp4 v[82:83], v58, v86 op_sel:[1,0,0]
	v_pk_fma_f32 v[148:149], v[80:81], s[54:55], v[148:149] op_sel_hi:[1,0,1]
	v_cvt_scalef32_pk_f32_fp4 v[80:81], v58, v86 op_sel:[0,1,0]
	v_pk_fma_f32 v[146:147], v[82:83], s[54:55], v[146:147] op_sel_hi:[1,0,1]
	v_cvt_scalef32_pk_f32_fp4 v[82:83], v58, v86 op_sel:[1,1,0]
	v_pk_fma_f32 v[144:145], v[80:81], s[54:55], v[144:145] op_sel_hi:[1,0,1]
	v_cvt_scalef32_pk_f32_fp4 v[80:81], v59, v86
	v_pk_fma_f32 v[142:143], v[82:83], s[54:55], v[142:143] op_sel_hi:[1,0,1]
	v_cvt_scalef32_pk_f32_fp4 v[82:83], v59, v86 op_sel:[1,0,0]
	v_pk_fma_f32 v[140:141], v[80:81], s[54:55], v[140:141] op_sel_hi:[1,0,1]
	v_cvt_scalef32_pk_f32_fp4 v[80:81], v59, v86 op_sel:[0,1,0]
	v_pk_fma_f32 v[138:139], v[82:83], s[54:55], v[138:139] op_sel_hi:[1,0,1]
	v_cvt_scalef32_pk_f32_fp4 v[82:83], v59, v86 op_sel:[1,1,0]
	v_pk_fma_f32 v[136:137], v[80:81], s[54:55], v[136:137] op_sel_hi:[1,0,1]
	v_pk_fma_f32 v[134:135], v[82:83], s[54:55], v[134:135] op_sel_hi:[1,0,1]
	v_lshl_add_u32 v87, s58, 10, v196
	v_lshl_add_u32 v88, s58, 7, v92
	global_load_dwordx4 v[56:59], v87, s[16:17] sc1
	global_load_ubyte v78, v88, s[14:15] offset:64
	s_waitcnt vmcnt(30)
	v_lshlrev_b32_e32 v86, 23, v79
	v_cvt_scalef32_pk_f32_fp4 v[80:81], v60, v86
	v_cvt_scalef32_pk_f32_fp4 v[82:83], v60, v86 op_sel:[1,0,0]
	v_pk_fma_f32 v[164:165], v[80:81], s[56:57], v[164:165] op_sel_hi:[1,0,1]
	v_cvt_scalef32_pk_f32_fp4 v[80:81], v60, v86 op_sel:[0,1,0]
	v_pk_fma_f32 v[162:163], v[82:83], s[56:57], v[162:163] op_sel_hi:[1,0,1]
	v_cvt_scalef32_pk_f32_fp4 v[82:83], v60, v86 op_sel:[1,1,0]
	v_pk_fma_f32 v[160:161], v[80:81], s[56:57], v[160:161] op_sel_hi:[1,0,1]
	v_cvt_scalef32_pk_f32_fp4 v[80:81], v61, v86
	v_pk_fma_f32 v[158:159], v[82:83], s[56:57], v[158:159] op_sel_hi:[1,0,1]
	v_cvt_scalef32_pk_f32_fp4 v[82:83], v61, v86 op_sel:[1,0,0]
	v_pk_fma_f32 v[156:157], v[80:81], s[56:57], v[156:157] op_sel_hi:[1,0,1]
	v_cvt_scalef32_pk_f32_fp4 v[80:81], v61, v86 op_sel:[0,1,0]
	v_pk_fma_f32 v[154:155], v[82:83], s[56:57], v[154:155] op_sel_hi:[1,0,1]
	v_cvt_scalef32_pk_f32_fp4 v[82:83], v61, v86 op_sel:[1,1,0]
	v_pk_fma_f32 v[152:153], v[80:81], s[56:57], v[152:153] op_sel_hi:[1,0,1]
	v_cvt_scalef32_pk_f32_fp4 v[80:81], v62, v86
	v_pk_fma_f32 v[150:151], v[82:83], s[56:57], v[150:151] op_sel_hi:[1,0,1]
	v_cvt_scalef32_pk_f32_fp4 v[82:83], v62, v86 op_sel:[1,0,0]
	v_pk_fma_f32 v[148:149], v[80:81], s[56:57], v[148:149] op_sel_hi:[1,0,1]
	v_cvt_scalef32_pk_f32_fp4 v[80:81], v62, v86 op_sel:[0,1,0]
	v_pk_fma_f32 v[146:147], v[82:83], s[56:57], v[146:147] op_sel_hi:[1,0,1]
	v_cvt_scalef32_pk_f32_fp4 v[82:83], v62, v86 op_sel:[1,1,0]
	v_pk_fma_f32 v[144:145], v[80:81], s[56:57], v[144:145] op_sel_hi:[1,0,1]
	v_cvt_scalef32_pk_f32_fp4 v[80:81], v63, v86
	v_pk_fma_f32 v[142:143], v[82:83], s[56:57], v[142:143] op_sel_hi:[1,0,1]
	v_cvt_scalef32_pk_f32_fp4 v[82:83], v63, v86 op_sel:[1,0,0]
	v_pk_fma_f32 v[140:141], v[80:81], s[56:57], v[140:141] op_sel_hi:[1,0,1]
	v_cvt_scalef32_pk_f32_fp4 v[80:81], v63, v86 op_sel:[0,1,0]
	v_pk_fma_f32 v[138:139], v[82:83], s[56:57], v[138:139] op_sel_hi:[1,0,1]
	v_cvt_scalef32_pk_f32_fp4 v[82:83], v63, v86 op_sel:[1,1,0]
	v_pk_fma_f32 v[136:137], v[80:81], s[56:57], v[136:137] op_sel_hi:[1,0,1]
	v_pk_fma_f32 v[134:135], v[82:83], s[56:57], v[134:135] op_sel_hi:[1,0,1]
	v_lshl_add_u32 v87, s59, 10, v196
	v_lshl_add_u32 v88, s59, 7, v92
	global_load_dwordx4 v[60:63], v87, s[16:17] sc1
	global_load_ubyte v79, v88, s[14:15] offset:64
	ds_bpermute_b32 v192, v194, v192
	ds_bpermute_b32 v193, v194, v193
	s_add_i32 s30, s30, 1
	s_waitcnt lgkmcnt(0)
	s_cmp_eq_u32 s30, 7
	s_cbranch_scc0 .Lp10_ne7
	v_mov_b32_e32 v192, v168
